# attention q-block transition: early Q prefetch plus a counted wait that excludes the O-store acknowledgements
# speedup vs baseline: 1.0050x; 1.0050x over previous
; #define LAS __attribute__((address_space(3)))
; __device__ __forceinline__ unsigned cvtpk(float lo, float hi) { const f32x2 v = {lo, hi}; const bf16x2_t b = __builtin_convertvector(v, bf16x2_t); return __builtin_bit_cast(unsigned, b); }
; __device__ __forceinline__ void attn_phase(LAS unsigned char* lds, KP kp, int wid0) {
;     ...
;             { const auto rr = __builtin_amdgcn_permlane32_swap(__float_as_uint(l_run), __float_as_uint(l_run), false, false); l_run = __uint_as_float(rr[0]) + __uint_as_float(rr[1]); }
;             {
;                 const float inv = 1.0f / l_run;
;                 LAS unsigned char* stg = lds + 45056 + wid * 4608;
; #pragma unroll
;                 for (int g = 0; g < 4; ++g) {
;                     u32x2 w; w.x = cvtpk(o0[4 * g] * inv, o0[4 * g + 1] * inv); w.y = cvtpk(o0[4 * g + 2] * inv, o0[4 * g + 3] * inv); *(LAS u32x2*)(stg + r32 * 144 + (8 * g + 4 * hi) * 2) = w;
;                     w.x = cvtpk(o1[4 * g] * inv, o1[4 * g + 1] * inv); w.y = cvtpk(o1[4 * g + 2] * inv, o1[4 * g + 3] * inv); *(LAS u32x2*)(stg + r32 * 144 + 64 + (8 * g + 4 * hi) * 2) = w;
;                 }
;                 asm volatile("s_waitcnt lgkmcnt(0)" ::: "memory");
; #pragma unroll
;                 for (int i = 0; i < 4; ++i) {
;                     const int row = i * 8 + (lane >> 3), ch = lane & 7, qq = qw0 + row;
;                     const u32x4 v = *(const LAS u32x4*)(stg + row * 144 + ch * 16);
;                     if (qq >= 0) *(u32x4*)(O + (size_t)(rowb + qq) * DM + h * 64 + ch * 8) = v;
;                 }
;                 asm volatile("s_waitcnt lgkmcnt(0)" ::: "memory");
;             }
.LBB0_466:
.LBB0_467:
	s_mov_b32 s6, 0
	v_mov_b32_e32 v1, v218
	s_nop 1
	v_permlane32_swap_b32_e32 v218, v1
	v_add_f32_e32 v1, v218, v1
	v_div_scale_f32 v10, s[4:5], v1, v1, 1.0
	v_rcp_f32_e32 v11, v10
	s_nop 0
	v_fma_f32 v12, -v10, v11, 1.0
	v_fmac_f32_e32 v11, v12, v11
	v_div_scale_f32 v12, vcc, 1.0, v1, 1.0
	v_mul_f32_e32 v13, v12, v11
	v_fma_f32 v48, -v10, v13, v12
	v_fmac_f32_e32 v13, v48, v11
	v_fma_f32 v10, -v10, v13, v12
	v_div_fmas_f32 v10, v10, v11, v13
	v_div_fixup_f32 v10, v10, v1, 1.0
	v_pk_mul_f32 v[12:13], v[32:33], v[10:11] op_sel_hi:[1,0]
	v_pk_mul_f32 v[32:33], v[34:35], v[10:11] op_sel_hi:[1,0]
	v_pk_mul_f32 v[16:17], v[16:17], v[10:11] op_sel_hi:[1,0]
	v_pk_mul_f32 v[18:19], v[18:19], v[10:11] op_sel_hi:[1,0]
	v_cvt_pk_bf16_f32 v12, v12, v13
	v_cvt_pk_bf16_f32 v13, v32, v33
	v_cvt_pk_bf16_f32 v16, v16, v17
	v_cvt_pk_bf16_f32 v17, v18, v19
	v_pk_mul_f32 v[18:19], v[36:37], v[10:11] op_sel_hi:[1,0]
	v_pk_mul_f32 v[32:33], v[38:39], v[10:11] op_sel_hi:[1,0]
	v_cvt_pk_bf16_f32 v18, v18, v19
	v_cvt_pk_bf16_f32 v19, v32, v33
	v_add_u32_e32 v1, 0xb000, v209
	ds_write2_b64 v1, v[12:13], v[18:19] offset1:2
	v_pk_mul_f32 v[12:13], v[20:21], v[10:11] op_sel_hi:[1,0]
	v_pk_mul_f32 v[18:19], v[22:23], v[10:11] op_sel_hi:[1,0]
	v_cvt_pk_bf16_f32 v12, v12, v13
	v_cvt_pk_bf16_f32 v13, v18, v19
	ds_write2_b64 v1, v[16:17], v[12:13] offset0:8 offset1:10
	v_pk_mul_f32 v[12:13], v[40:41], v[10:11] op_sel_hi:[1,0]
	v_pk_mul_f32 v[16:17], v[42:43], v[10:11] op_sel_hi:[1,0]
	v_cvt_pk_bf16_f32 v12, v12, v13
	v_cvt_pk_bf16_f32 v13, v16, v17
	v_pk_mul_f32 v[16:17], v[24:25], v[10:11] op_sel_hi:[1,0]
	v_pk_mul_f32 v[18:19], v[26:27], v[10:11] op_sel_hi:[1,0]
	v_cvt_pk_bf16_f32 v16, v16, v17
	v_cvt_pk_bf16_f32 v17, v18, v19
	v_pk_mul_f32 v[18:19], v[44:45], v[10:11] op_sel_hi:[1,0]
	v_pk_mul_f32 v[20:21], v[46:47], v[10:11] op_sel_hi:[1,0]
	v_cvt_pk_bf16_f32 v18, v18, v19
	v_cvt_pk_bf16_f32 v19, v20, v21
	ds_write2_b64 v1, v[12:13], v[18:19] offset0:4 offset1:6
	v_pk_mul_f32 v[12:13], v[28:29], v[10:11] op_sel_hi:[1,0]
	v_pk_mul_f32 v[10:11], v[30:31], v[10:11] op_sel_hi:[1,0]
	v_cvt_pk_bf16_f32 v12, v12, v13
	v_cvt_pk_bf16_f32 v13, v10, v11
	ds_write2_b64 v1, v[16:17], v[12:13] offset0:12 offset1:14
	s_waitcnt lgkmcnt(0)
	v_cmp_lt_i32_e32 vcc, -1, v175
	s_and_saveexec_b64 s[4:5], vcc
	s_cbranch_execz .LBB0_469
	s_add_i32 s6, s6, 2
	v_add_u32_e32 v10, v216, v175
	v_ashrrev_i32_e32 v11, 31, v10
	v_lshlrev_b64 v[10:11], 11, v[10:11]
	v_lshl_add_u64 v[16:17], v[180:181], 0, v[10:11]
	ds_read_b128 v[10:13], v212 offset:45056
	s_waitcnt lgkmcnt(0)
	global_store_dwordx4 v[16:17], v[10:13], off
	s_nop 1
	v_add_u32_e32 v10, v217, v175
	v_ashrrev_i32_e32 v11, 31, v10
	v_lshlrev_b64 v[10:11], 11, v[10:11]
	v_lshl_add_u64 v[16:17], v[180:181], 0, v[10:11]
	ds_read_b128 v[10:13], v212 offset:46208
	s_waitcnt lgkmcnt(0)
	global_store_dwordx4 v[16:17], v[10:13], off
.LBB0_469:
	s_or_b64 exec, exec, s[4:5]
	v_add_u32_e32 v1, v175, v207
	v_cmp_lt_i32_e32 vcc, -1, v1
	s_and_saveexec_b64 s[4:5], vcc
	s_cbranch_execz .LBB0_471
	s_add_i32 s6, s6, 1
	v_add_u32_e32 v10, s1, v1
	v_ashrrev_i32_e32 v11, 31, v10
	v_lshlrev_b64 v[10:11], 11, v[10:11]
	v_lshl_add_u64 v[16:17], v[180:181], 0, v[10:11]
	ds_read_b128 v[10:13], v212 offset:47360
	s_waitcnt lgkmcnt(0)
	global_store_dwordx4 v[16:17], v[10:13], off
.LBB0_471:
	s_or_b64 exec, exec, s[4:5]
	v_add_u32_e32 v1, v175, v208
	v_cmp_lt_i32_e32 vcc, -1, v1
	s_and_saveexec_b64 s[4:5], vcc
	s_cbranch_execz .LBB0_473
	s_add_i32 s6, s6, 1
	v_add_u32_e32 v10, s1, v1
	v_ashrrev_i32_e32 v11, 31, v10
	v_lshlrev_b64 v[10:11], 11, v[10:11]
	v_lshl_add_u64 v[16:17], v[180:181], 0, v[10:11]
	ds_read_b128 v[10:13], v212 offset:48512
	s_waitcnt lgkmcnt(0)
	global_store_dwordx4 v[16:17], v[10:13], off
.LBB0_473:
	s_or_b64 exec, exec, s[4:5]
	s_waitcnt lgkmcnt(0)
	s_add_i32 s43, s43, 1
	s_cmp_eq_u32 s43, 9
	s_cbranch_scc1 .LBB0_410
	s_cmp_lg_u32 s6, 4
	s_cbranch_scc1 .Lqt_n4
	s_waitcnt vmcnt(4)
	s_branch .Lqt_done
.Lqt_n4:
	s_cmp_lg_u32 s6, 3
	s_cbranch_scc1 .Lqt_n3
	s_waitcnt vmcnt(3)
	s_branch .Lqt_done
.Lqt_n3:
	s_cmp_lg_u32 s6, 2
	s_cbranch_scc1 .Lqt_n2
	s_waitcnt vmcnt(2)
	s_branch .Lqt_done
.Lqt_n2:
	s_cmp_lg_u32 s6, 1
	s_cbranch_scc1 .Lqt_n1
	s_waitcnt vmcnt(1)
	s_branch .Lqt_done

; #define LAS __attribute__((address_space(3)))
; __device__ __forceinline__ unsigned cvtpk(float lo, float hi) { const f32x2 v = {lo, hi}; const bf16x2_t b = __builtin_convertvector(v, bf16x2_t); return __builtin_bit_cast(unsigned, b); }
; __device__ __forceinline__ void attn_phase(LAS unsigned char* lds, KP kp, int wid0) {
;     ...
;             { const auto rr = __builtin_amdgcn_permlane32_swap(__float_as_uint(l_run), __float_as_uint(l_run), false, false); l_run = __uint_as_float(rr[0]) + __uint_as_float(rr[1]); }
;             {
;                 const float inv = 1.0f / l_run;
;                 LAS unsigned char* stg = lds + 45056 + wid * 4608;
; #pragma unroll
;                 for (int g = 0; g < 4; ++g) {
;                     u32x2 w; w.x = cvtpk(o0[4 * g] * inv, o0[4 * g + 1] * inv); w.y = cvtpk(o0[4 * g + 2] * inv, o0[4 * g + 3] * inv); *(LAS u32x2*)(stg + r32 * 144 + (8 * g + 4 * hi) * 2) = w;
;                     w.x = cvtpk(o1[4 * g] * inv, o1[4 * g + 1] * inv); w.y = cvtpk(o1[4 * g + 2] * inv, o1[4 * g + 3] * inv); *(LAS u32x2*)(stg + r32 * 144 + 64 + (8 * g + 4 * hi) * 2) = w;
;                 }
;                 asm volatile("s_waitcnt lgkmcnt(0)" ::: "memory");
; #pragma unroll
;                 for (int i = 0; i < 4; ++i) {
;                     const int row = i * 8 + (lane >> 3), ch = lane & 7, qq = qw0 + row;
;                     const u32x4 v = *(const LAS u32x4*)(stg + row * 144 + ch * 16);
;                     if (qq >= 0) *(u32x4*)(O + (size_t)(rowb + qq) * DM + h * 64 + ch * 8) = v;
;                 }
;                 asm volatile("s_waitcnt lgkmcnt(0)" ::: "memory");
;             }
.Lqt_done:
	v_mov_b64_e32 v[130:131], v[4:5]
	v_mov_b64_e32 v[134:135], v[8:9]
	v_mov_b64_e32 v[128:129], v[2:3]
	v_mov_b64_e32 v[132:133], v[6:7]
	v_mov_b64_e32 v[188:189], v[14:15]
	v_mov_b64_e32 v[190:191], v[192:193]
	s_branch .LBB0_414
